# K-loop trims + first trip of every K-loop peeled with inline-0 SrcC on the first MFMA of each accumulator: the 128-register clear per GEMM unit is gone
# speedup vs baseline: 1.0032x; 1.0008x over previous
.LBB0_269:
	s_ashr_i32 s25, s24, 31
	s_lshl_b64 s[26:27], s[24:25], 20
	s_add_u32 s26, s36, s26
	s_addc_u32 s27, s37, s27
	s_and_b64 s[28:29], s[6:7], exec
	s_cselect_b32 s2, s27, s31
	s_cselect_b32 s25, s26, s30
	s_ashr_i32 s23, s22, 31
	s_lshl_b64 s[28:29], s[22:23], 20
	s_add_u32 s28, s38, s28
	s_addc_u32 s29, s39, s29
	s_and_b64 s[34:35], s[6:7], exec
	s_cselect_b32 s23, s29, s57
	s_cselect_b32 s54, s28, s56
	s_ashr_i32 s1, s0, 31
	s_lshl_b64 s[34:35], s[0:1], 13
	s_add_u32 s1, s56, 0x100
	s_addc_u32 s55, s57, 0
	s_add_u32 s8, s30, 0x80080
	s_waitcnt vmcnt(0)
	v_lshl_add_u64 v[66:67], v[168:169], 0, s[34:35]
	s_addc_u32 s9, s31, 0
	s_mov_b32 s56, -2
	s_cmp_eq_u32 s56, 28
	s_cselect_b64 s[30:31], -1, 0
	s_add_u32 s34, s8, 0xfff80080
	s_addc_u32 s35, s9, -1
	s_and_b64 s[30:31], s[30:31], exec
	s_cselect_b32 s35, s2, s35
	s_cselect_b32 s34, s25, s34
	s_cselect_b32 s31, s23, s55
	s_cselect_b32 s30, s54, s1
	s_add_i32 s57, 0, 0x10000
	v_add_u32_e32 v72, s57, v181
	s_add_i32 s62, 0, 0x14000
	ds_read_b128 v[68:71], v72
	ds_read_b128 v[82:85], v72 offset:1024
	ds_read_b128 v[86:89], v72 offset:2048
	ds_read_b128 v[146:149], v72 offset:3072
	v_add_u32_e32 v72, s62, v181
	ds_read_b128 v[150:153], v72
	ds_read_b128 v[154:157], v72 offset:1024
	ds_read_b128 v[158:161], v72 offset:2048
	ds_read_b128 v[202:205], v72 offset:3072
	v_lshl_add_u64 v[72:73], s[8:9], 0, v[172:173]
	s_add_i32 m0, s41, 0xc000
	ds_read_b128 v[206:209], v199
	ds_read_b128 v[210:213], v199 offset:1024
	ds_read_b128 v[214:217], v199 offset:2048
	ds_read_b128 v[226:229], v199 offset:3072
	ds_read_b128 v[230:233], v199 offset:4096
	ds_read_b128 v[234:237], v199 offset:5120
	ds_read_b128 v[238:241], v199 offset:6144
	ds_read_b128 v[242:245], v199 offset:7168
	global_load_lds_dwordx4 v[72:73], off
	v_lshl_add_u64 v[72:73], s[8:9], 0, v[170:171]
	s_add_i32 m0, s41, 0xe000
	s_nop 0
	global_load_lds_dwordx4 v[72:73], off
	s_waitcnt vmcnt(8)
	s_waitcnt lgkmcnt(0)
	s_barrier
	s_setprio 1
	v_mfma_f32_16x16x32_bf16 v[142:145], v[68:71], v[206:209], 0
	v_mfma_f32_16x16x32_bf16 v[138:141], v[86:89], v[206:209], 0
	v_mfma_f32_16x16x32_bf16 v[126:129], v[68:71], v[214:217], 0
	v_mfma_f32_16x16x32_bf16 v[122:125], v[86:89], v[214:217], 0
	v_mfma_f32_16x16x32_bf16 v[110:113], v[68:71], v[230:233], 0
	v_mfma_f32_16x16x32_bf16 v[106:109], v[86:89], v[230:233], 0
	v_mfma_f32_16x16x32_bf16 v[94:97], v[68:71], v[238:241], 0
	v_mfma_f32_16x16x32_bf16 v[90:93], v[86:89], v[238:241], 0
	v_mfma_f32_16x16x32_bf16 v[142:145], v[82:85], v[210:213], v[142:145]
	v_mfma_f32_16x16x32_bf16 v[138:141], v[146:149], v[210:213], v[138:141]
	v_mfma_f32_16x16x32_bf16 v[126:129], v[82:85], v[226:229], v[126:129]
	v_mfma_f32_16x16x32_bf16 v[122:125], v[146:149], v[226:229], v[122:125]
	v_mfma_f32_16x16x32_bf16 v[110:113], v[82:85], v[234:237], v[110:113]
	v_mfma_f32_16x16x32_bf16 v[106:109], v[146:149], v[234:237], v[106:109]
	v_mfma_f32_16x16x32_bf16 v[94:97], v[82:85], v[242:245], v[94:97]
	v_mfma_f32_16x16x32_bf16 v[90:93], v[146:149], v[242:245], v[90:93]
	v_mfma_f32_16x16x32_bf16 v[134:137], v[150:153], v[206:209], 0
	v_mfma_f32_16x16x32_bf16 v[130:133], v[158:161], v[206:209], 0
	v_mfma_f32_16x16x32_bf16 v[118:121], v[150:153], v[214:217], 0
	v_mfma_f32_16x16x32_bf16 v[114:117], v[158:161], v[214:217], 0
	v_mfma_f32_16x16x32_bf16 v[102:105], v[150:153], v[230:233], 0
	v_mfma_f32_16x16x32_bf16 v[98:101], v[158:161], v[230:233], 0
	v_mfma_f32_16x16x32_bf16 v[78:81], v[150:153], v[238:241], 0
	v_mfma_f32_16x16x32_bf16 v[72:75], v[158:161], v[238:241], 0
	v_mfma_f32_16x16x32_bf16 v[134:137], v[154:157], v[210:213], v[134:137]
	v_mfma_f32_16x16x32_bf16 v[130:133], v[202:205], v[210:213], v[130:133]
	v_mfma_f32_16x16x32_bf16 v[118:121], v[154:157], v[226:229], v[118:121]
	v_mfma_f32_16x16x32_bf16 v[114:117], v[202:205], v[226:229], v[114:117]
	v_mfma_f32_16x16x32_bf16 v[102:105], v[154:157], v[234:237], v[102:105]
	v_mfma_f32_16x16x32_bf16 v[98:101], v[202:205], v[234:237], v[98:101]
	v_mfma_f32_16x16x32_bf16 v[78:81], v[154:157], v[242:245], v[78:81]
	v_mfma_f32_16x16x32_bf16 v[72:75], v[202:205], v[242:245], v[72:75]
	s_setprio 0
	s_barrier
	s_add_i32 s57, s57, s40
	v_lshl_add_u64 v[178:179], s[30:31], 0, v[0:1]
	s_mov_b32 m0, s57
	ds_read_b128 v[206:209], v199 offset:16384
	ds_read_b128 v[210:213], v199 offset:17408
	ds_read_b128 v[214:217], v199 offset:18432
	ds_read_b128 v[226:229], v199 offset:19456
	ds_read_b128 v[230:233], v199 offset:20480
	ds_read_b128 v[234:237], v199 offset:21504
	ds_read_b128 v[238:241], v199 offset:22528
	ds_read_b128 v[242:245], v199 offset:23552
	global_load_lds_dwordx4 v[178:179], off
	s_add_i32 m0, s57, 0x2000
	s_add_u32 s60, s30, 0x80000
	v_lshl_add_u64 v[250:251], s[30:31], 0, v[162:163]
	s_addc_u32 s61, s31, 0
	s_add_i32 s57, s62, s40
	global_load_lds_dwordx4 v[250:251], off
	v_lshl_add_u64 v[76:77], s[60:61], 0, v[0:1]
	s_mov_b32 m0, s57
	v_lshl_add_u64 v[252:253], s[34:35], 0, v[166:167]
	global_load_lds_dwordx4 v[76:77], off
	v_lshl_add_u64 v[76:77], s[60:61], 0, v[162:163]
	s_add_i32 m0, s57, 0x2000
	v_lshl_add_u64 v[220:221], s[34:35], 0, v[164:165]
	global_load_lds_dwordx4 v[76:77], off
	s_mov_b32 m0, s41
	s_nop 0
	global_load_lds_dwordx4 v[252:253], off
	s_mov_b32 m0, s42
	s_nop 0
	global_load_lds_dwordx4 v[220:221], off
	s_waitcnt vmcnt(8)
	s_waitcnt lgkmcnt(0)
	s_barrier
	s_setprio 1
	v_mfma_f32_16x16x32_bf16 v[62:65], v[68:71], v[206:209], 0
	v_mfma_f32_16x16x32_bf16 v[58:61], v[86:89], v[206:209], 0
	v_mfma_f32_16x16x32_bf16 v[46:49], v[68:71], v[214:217], 0
	v_mfma_f32_16x16x32_bf16 v[42:45], v[86:89], v[214:217], 0
	v_mfma_f32_16x16x32_bf16 v[30:33], v[68:71], v[230:233], 0
	v_mfma_f32_16x16x32_bf16 v[26:29], v[86:89], v[230:233], 0
	v_mfma_f32_16x16x32_bf16 v[14:17], v[68:71], v[238:241], 0
	v_mfma_f32_16x16x32_bf16 v[10:13], v[86:89], v[238:241], 0
	v_mfma_f32_16x16x32_bf16 v[62:65], v[82:85], v[210:213], v[62:65]
	v_mfma_f32_16x16x32_bf16 v[58:61], v[146:149], v[210:213], v[58:61]
	v_mfma_f32_16x16x32_bf16 v[46:49], v[82:85], v[226:229], v[46:49]
	v_mfma_f32_16x16x32_bf16 v[42:45], v[146:149], v[226:229], v[42:45]
	v_mfma_f32_16x16x32_bf16 v[30:33], v[82:85], v[234:237], v[30:33]
	v_mfma_f32_16x16x32_bf16 v[26:29], v[146:149], v[234:237], v[26:29]
	v_mfma_f32_16x16x32_bf16 v[14:17], v[82:85], v[242:245], v[14:17]
	v_mfma_f32_16x16x32_bf16 v[10:13], v[146:149], v[242:245], v[10:13]
	v_mfma_f32_16x16x32_bf16 v[54:57], v[150:153], v[206:209], 0
	v_mfma_f32_16x16x32_bf16 v[50:53], v[158:161], v[206:209], 0
	v_mfma_f32_16x16x32_bf16 v[38:41], v[150:153], v[214:217], 0
	v_mfma_f32_16x16x32_bf16 v[34:37], v[158:161], v[214:217], 0
	v_mfma_f32_16x16x32_bf16 v[22:25], v[150:153], v[230:233], 0
	v_mfma_f32_16x16x32_bf16 v[18:21], v[158:161], v[230:233], 0
	v_mfma_f32_16x16x32_bf16 v[6:9], v[150:153], v[238:241], 0
	v_mfma_f32_16x16x32_bf16 v[2:5], v[158:161], v[238:241], 0
	v_mfma_f32_16x16x32_bf16 v[54:57], v[154:157], v[210:213], v[54:57]
	v_mfma_f32_16x16x32_bf16 v[50:53], v[202:205], v[210:213], v[50:53]
	v_mfma_f32_16x16x32_bf16 v[38:41], v[154:157], v[226:229], v[38:41]
	v_mfma_f32_16x16x32_bf16 v[34:37], v[202:205], v[226:229], v[34:37]
	v_mfma_f32_16x16x32_bf16 v[22:25], v[154:157], v[234:237], v[22:25]
	v_mfma_f32_16x16x32_bf16 v[18:21], v[202:205], v[234:237], v[18:21]
	v_mfma_f32_16x16x32_bf16 v[6:9], v[154:157], v[242:245], v[6:9]
	v_mfma_f32_16x16x32_bf16 v[2:5], v[202:205], v[242:245], v[2:5]
	s_setprio 0
	s_barrier
	s_add_i32 s57, 0, 0x18000
	v_add_u32_e32 v76, s57, v181
	s_add_i32 s60, 0, 0x1c000
	ds_read_b128 v[68:71], v76
	ds_read_b128 v[82:85], v76 offset:1024
	ds_read_b128 v[86:89], v76 offset:2048
	ds_read_b128 v[146:149], v76 offset:3072
	v_add_u32_e32 v76, s60, v181
	ds_read_b128 v[150:153], v76
	ds_read_b128 v[154:157], v76 offset:1024
	ds_read_b128 v[158:161], v76 offset:2048
	ds_read_b128 v[202:205], v76 offset:3072
	s_add_u32 s34, s34, 0x80000
	s_addc_u32 s35, s35, 0
	s_mov_b32 m0, s43
	v_lshl_add_u64 v[76:77], s[34:35], 0, v[166:167]
	ds_read_b128 v[206:209], v199 offset:32768
	ds_read_b128 v[210:213], v199 offset:33792
	ds_read_b128 v[214:217], v199 offset:34816
	ds_read_b128 v[226:229], v199 offset:35840
	ds_read_b128 v[230:233], v199 offset:36864
	ds_read_b128 v[234:237], v199 offset:37888
	ds_read_b128 v[238:241], v199 offset:38912
	ds_read_b128 v[242:245], v199 offset:39936
	global_load_lds_dwordx4 v[76:77], off
	v_lshl_add_u64 v[76:77], s[34:35], 0, v[164:165]
	s_mov_b32 m0, s44
	s_nop 0
	global_load_lds_dwordx4 v[76:77], off
	s_waitcnt vmcnt(8)
	s_waitcnt lgkmcnt(0)
	s_barrier
	s_setprio 1
	v_mfma_f32_16x16x32_bf16 v[142:145], v[68:71], v[206:209], v[142:145]
	v_mfma_f32_16x16x32_bf16 v[138:141], v[86:89], v[206:209], v[138:141]
	v_mfma_f32_16x16x32_bf16 v[126:129], v[68:71], v[214:217], v[126:129]
	v_mfma_f32_16x16x32_bf16 v[122:125], v[86:89], v[214:217], v[122:125]
	v_mfma_f32_16x16x32_bf16 v[110:113], v[68:71], v[230:233], v[110:113]
	v_mfma_f32_16x16x32_bf16 v[106:109], v[86:89], v[230:233], v[106:109]
	v_mfma_f32_16x16x32_bf16 v[94:97], v[68:71], v[238:241], v[94:97]
	v_mfma_f32_16x16x32_bf16 v[90:93], v[86:89], v[238:241], v[90:93]
	v_mfma_f32_16x16x32_bf16 v[142:145], v[82:85], v[210:213], v[142:145]
	v_mfma_f32_16x16x32_bf16 v[138:141], v[146:149], v[210:213], v[138:141]
	v_mfma_f32_16x16x32_bf16 v[126:129], v[82:85], v[226:229], v[126:129]
	v_mfma_f32_16x16x32_bf16 v[122:125], v[146:149], v[226:229], v[122:125]
	v_mfma_f32_16x16x32_bf16 v[110:113], v[82:85], v[234:237], v[110:113]
	v_mfma_f32_16x16x32_bf16 v[106:109], v[146:149], v[234:237], v[106:109]
	v_mfma_f32_16x16x32_bf16 v[94:97], v[82:85], v[242:245], v[94:97]
	v_mfma_f32_16x16x32_bf16 v[90:93], v[146:149], v[242:245], v[90:93]
	v_mfma_f32_16x16x32_bf16 v[134:137], v[150:153], v[206:209], v[134:137]
	v_mfma_f32_16x16x32_bf16 v[130:133], v[158:161], v[206:209], v[130:133]
	v_mfma_f32_16x16x32_bf16 v[118:121], v[150:153], v[214:217], v[118:121]
	v_mfma_f32_16x16x32_bf16 v[114:117], v[158:161], v[214:217], v[114:117]
	v_mfma_f32_16x16x32_bf16 v[102:105], v[150:153], v[230:233], v[102:105]
	v_mfma_f32_16x16x32_bf16 v[98:101], v[158:161], v[230:233], v[98:101]
	v_mfma_f32_16x16x32_bf16 v[76:79], v[150:153], v[238:241], v[78:81]
	v_mfma_f32_16x16x32_bf16 v[72:75], v[158:161], v[238:241], v[72:75]
	v_mfma_f32_16x16x32_bf16 v[134:137], v[154:157], v[210:213], v[134:137]
	v_mfma_f32_16x16x32_bf16 v[130:133], v[202:205], v[210:213], v[130:133]
	v_mfma_f32_16x16x32_bf16 v[118:121], v[154:157], v[226:229], v[118:121]
	v_mfma_f32_16x16x32_bf16 v[114:117], v[202:205], v[226:229], v[114:117]
	v_mfma_f32_16x16x32_bf16 v[102:105], v[154:157], v[234:237], v[102:105]
	v_mfma_f32_16x16x32_bf16 v[98:101], v[202:205], v[234:237], v[98:101]
	v_mfma_f32_16x16x32_bf16 v[78:81], v[154:157], v[242:245], v[76:79]
	v_mfma_f32_16x16x32_bf16 v[74:77], v[202:205], v[242:245], v[72:75]
	s_setprio 0
	s_barrier
	s_add_i32 s34, s57, s40
	v_lshl_add_u64 v[72:73], v[178:179], 0, s[96:97]
	s_mov_b32 m0, s34
	ds_read_b128 v[206:209], v199 offset:49152
	ds_read_b128 v[210:213], v199 offset:50176
	ds_read_b128 v[214:217], v199 offset:51200
	ds_read_b128 v[226:229], v199 offset:52224
	ds_read_b128 v[230:233], v199 offset:53248
	ds_read_b128 v[234:237], v199 offset:54272
	ds_read_b128 v[238:241], v199 offset:55296
	ds_read_b128 v[242:245], v199 offset:56320
	global_load_lds_dwordx4 v[72:73], off
	s_add_i32 m0, s34, 0x2000
	s_add_u32 s30, s30, 0x80080
	v_lshl_add_u64 v[72:73], v[250:251], 0, s[96:97]
	s_addc_u32 s31, s31, 0
	s_add_i32 s34, s60, s40
	global_load_lds_dwordx4 v[72:73], off
	v_lshl_add_u64 v[72:73], s[30:31], 0, v[0:1]
	s_mov_b32 m0, s34
	s_nop 0
	global_load_lds_dwordx4 v[72:73], off
	v_lshl_add_u64 v[72:73], s[30:31], 0, v[162:163]
	s_add_i32 m0, s34, 0x2000
	s_nop 0
	global_load_lds_dwordx4 v[72:73], off
	v_lshl_add_u64 v[72:73], v[252:253], 0, s[96:97]
	s_mov_b32 m0, s47
	s_nop 0
	global_load_lds_dwordx4 v[72:73], off
	v_lshl_add_u64 v[72:73], v[220:221], 0, s[96:97]
	s_mov_b32 m0, s50
	s_nop 0
	global_load_lds_dwordx4 v[72:73], off
	s_waitcnt vmcnt(8)
	s_waitcnt lgkmcnt(0)
	s_barrier
	s_setprio 1
	v_mfma_f32_16x16x32_bf16 v[62:65], v[68:71], v[206:209], v[62:65]
	v_mfma_f32_16x16x32_bf16 v[58:61], v[86:89], v[206:209], v[58:61]
	v_mfma_f32_16x16x32_bf16 v[46:49], v[68:71], v[214:217], v[46:49]
	v_mfma_f32_16x16x32_bf16 v[42:45], v[86:89], v[214:217], v[42:45]
	v_mfma_f32_16x16x32_bf16 v[30:33], v[68:71], v[230:233], v[30:33]
	v_mfma_f32_16x16x32_bf16 v[26:29], v[86:89], v[230:233], v[26:29]
	v_mfma_f32_16x16x32_bf16 v[14:17], v[68:71], v[238:241], v[14:17]
	v_mfma_f32_16x16x32_bf16 v[10:13], v[86:89], v[238:241], v[10:13]
	v_mfma_f32_16x16x32_bf16 v[62:65], v[82:85], v[210:213], v[62:65]
	v_mfma_f32_16x16x32_bf16 v[58:61], v[146:149], v[210:213], v[58:61]
	v_mfma_f32_16x16x32_bf16 v[46:49], v[82:85], v[226:229], v[46:49]
	v_mfma_f32_16x16x32_bf16 v[42:45], v[146:149], v[226:229], v[42:45]
	v_mfma_f32_16x16x32_bf16 v[30:33], v[82:85], v[234:237], v[30:33]
	v_mfma_f32_16x16x32_bf16 v[26:29], v[146:149], v[234:237], v[26:29]
	v_mfma_f32_16x16x32_bf16 v[14:17], v[82:85], v[242:245], v[14:17]
	v_mfma_f32_16x16x32_bf16 v[10:13], v[146:149], v[242:245], v[10:13]
	v_mfma_f32_16x16x32_bf16 v[54:57], v[150:153], v[206:209], v[54:57]
	v_mfma_f32_16x16x32_bf16 v[50:53], v[158:161], v[206:209], v[50:53]
	v_mfma_f32_16x16x32_bf16 v[38:41], v[150:153], v[214:217], v[38:41]
	v_mfma_f32_16x16x32_bf16 v[34:37], v[158:161], v[214:217], v[34:37]
	v_mfma_f32_16x16x32_bf16 v[22:25], v[150:153], v[230:233], v[22:25]
	v_mfma_f32_16x16x32_bf16 v[18:21], v[158:161], v[230:233], v[18:21]
	v_mfma_f32_16x16x32_bf16 v[6:9], v[150:153], v[238:241], v[6:9]
	v_mfma_f32_16x16x32_bf16 v[2:5], v[158:161], v[238:241], v[2:5]
	v_mfma_f32_16x16x32_bf16 v[54:57], v[154:157], v[210:213], v[54:57]
	v_mfma_f32_16x16x32_bf16 v[50:53], v[202:205], v[210:213], v[50:53]
	v_mfma_f32_16x16x32_bf16 v[38:41], v[154:157], v[226:229], v[38:41]
	v_mfma_f32_16x16x32_bf16 v[34:37], v[202:205], v[226:229], v[34:37]
	v_mfma_f32_16x16x32_bf16 v[22:25], v[154:157], v[234:237], v[22:25]
	v_mfma_f32_16x16x32_bf16 v[18:21], v[202:205], v[234:237], v[18:21]
	v_mfma_f32_16x16x32_bf16 v[6:9], v[154:157], v[242:245], v[6:9]
	v_mfma_f32_16x16x32_bf16 v[2:5], v[202:205], v[242:245], v[2:5]
	s_setprio 0
	s_barrier
	s_add_i32 s56, s56, 2
	s_add_u32 s1, s1, 0x100
	s_addc_u32 s55, s55, 0
	s_add_u32 s8, s8, 0x100
	s_addc_u32 s9, s9, 0
	s_cmp_gt_u32 s56, 29
	s_cbranch_scc1 .LBB0_273
	s_branch .LBB0_271

.LBB0_616:
	s_ashr_i32 s27, s26, 31
	s_lshl_b64 s[28:29], s[26:27], 20
	s_add_u32 s28, s2, s28
	s_addc_u32 s29, s38, s29
	s_and_b64 s[30:31], s[6:7], exec
	s_cselect_b32 s21, s29, s35
	s_cselect_b32 s23, s28, s34
	s_ashr_i32 s25, s24, 31
	s_lshl_b64 s[30:31], s[24:25], 20
	s_add_u32 s30, s39, s30
	s_addc_u32 s31, s40, s31
	s_and_b64 s[36:37], s[6:7], exec
	s_cselect_b32 s25, s31, s9
	s_cselect_b32 s27, s30, s8
	s_add_u32 s61, s8, 0x100
	s_addc_u32 s62, s9, 0
	s_add_u32 s8, s34, 0x80080
	s_addc_u32 s9, s35, 0
	s_mov_b32 s63, -2
	s_add_u32 s34, s8, 0xfff80080
	s_addc_u32 s35, s9, -1
	s_add_i32 s64, 0, 0x10000
	s_cmp_eq_u32 s63, 28
	s_cselect_b32 s37, s21, s35
	s_cselect_b32 s36, s23, s34
	v_add_u32_e32 v0, s64, v212
	s_cselect_b32 s35, s25, s62
	s_cselect_b32 s34, s27, s61
	s_add_i32 s66, 0, 0x14000
	ds_read_b128 v[66:69], v0
	ds_read_b128 v[70:73], v0 offset:1024
	ds_read_b128 v[74:77], v0 offset:2048
	ds_read_b128 v[78:81], v0 offset:3072
	v_add_u32_e32 v0, s66, v212
	ds_read_b128 v[130:133], v0
	ds_read_b128 v[142:145], v0 offset:1024
	ds_read_b128 v[146:149], v0 offset:2048
	ds_read_b128 v[158:161], v0 offset:3072
	v_lshl_add_u64 v[220:221], s[8:9], 0, v[190:191]
	s_add_i32 m0, s42, 0xc000
	ds_read_b128 v[162:165], v215
	ds_read_b128 v[166:169], v215 offset:1024
	ds_read_b128 v[170:173], v215 offset:2048
	ds_read_b128 v[192:195], v215 offset:3072
	ds_read_b128 v[196:199], v215 offset:4096
	ds_read_b128 v[200:203], v215 offset:5120
	ds_read_b128 v[204:207], v215 offset:6144
	ds_read_b128 v[208:211], v215 offset:7168
	global_load_lds_dwordx4 v[220:221], off
	v_lshl_add_u64 v[220:221], s[8:9], 0, v[188:189]
	s_add_i32 m0, s42, 0xe000
	s_nop 0
	global_load_lds_dwordx4 v[220:221], off
	s_waitcnt vmcnt(8)
	s_waitcnt lgkmcnt(0)
	s_barrier
	s_setprio 1
	v_mfma_f32_16x16x32_bf16 v[154:157], v[66:69], v[162:165], 0
	v_mfma_f32_16x16x32_bf16 v[150:153], v[74:77], v[162:165], 0
	v_mfma_f32_16x16x32_bf16 v[138:141], v[66:69], v[170:173], 0
	v_mfma_f32_16x16x32_bf16 v[134:137], v[74:77], v[170:173], 0
	v_mfma_f32_16x16x32_bf16 v[110:113], v[66:69], v[196:199], 0
	v_mfma_f32_16x16x32_bf16 v[106:109], v[74:77], v[196:199], 0
	v_mfma_f32_16x16x32_bf16 v[94:97], v[66:69], v[204:207], 0
	v_mfma_f32_16x16x32_bf16 v[90:93], v[74:77], v[204:207], 0
	v_mfma_f32_16x16x32_bf16 v[154:157], v[70:73], v[166:169], v[154:157]
	v_mfma_f32_16x16x32_bf16 v[150:153], v[78:81], v[166:169], v[150:153]
	v_mfma_f32_16x16x32_bf16 v[138:141], v[70:73], v[192:195], v[138:141]
	v_mfma_f32_16x16x32_bf16 v[134:137], v[78:81], v[192:195], v[134:137]
	v_mfma_f32_16x16x32_bf16 v[110:113], v[70:73], v[200:203], v[110:113]
	v_mfma_f32_16x16x32_bf16 v[106:109], v[78:81], v[200:203], v[106:109]
	v_mfma_f32_16x16x32_bf16 v[94:97], v[70:73], v[208:211], v[94:97]
	v_mfma_f32_16x16x32_bf16 v[90:93], v[78:81], v[208:211], v[90:93]
	v_mfma_f32_16x16x32_bf16 v[126:129], v[130:133], v[162:165], 0
	v_mfma_f32_16x16x32_bf16 v[114:117], v[146:149], v[162:165], 0
	v_mfma_f32_16x16x32_bf16 v[122:125], v[130:133], v[170:173], 0
	v_mfma_f32_16x16x32_bf16 v[118:121], v[146:149], v[170:173], 0
	v_mfma_f32_16x16x32_bf16 v[102:105], v[130:133], v[196:199], 0
	v_mfma_f32_16x16x32_bf16 v[98:101], v[146:149], v[196:199], 0
	v_mfma_f32_16x16x32_bf16 v[86:89], v[130:133], v[204:207], 0
	v_mfma_f32_16x16x32_bf16 v[82:85], v[146:149], v[204:207], 0
	v_mfma_f32_16x16x32_bf16 v[126:129], v[142:145], v[166:169], v[126:129]
	v_mfma_f32_16x16x32_bf16 v[114:117], v[158:161], v[166:169], v[114:117]
	v_mfma_f32_16x16x32_bf16 v[122:125], v[142:145], v[192:195], v[122:125]
	v_mfma_f32_16x16x32_bf16 v[118:121], v[158:161], v[192:195], v[118:121]
	v_mfma_f32_16x16x32_bf16 v[102:105], v[142:145], v[200:203], v[102:105]
	v_mfma_f32_16x16x32_bf16 v[98:101], v[158:161], v[200:203], v[98:101]
	v_mfma_f32_16x16x32_bf16 v[86:89], v[142:145], v[208:211], v[86:89]
	v_mfma_f32_16x16x32_bf16 v[82:85], v[158:161], v[208:211], v[82:85]
	s_setprio 0
	s_barrier
	s_add_i32 s64, s64, s41
	v_lshl_add_u64 v[220:221], s[34:35], 0, v[182:183]
	s_mov_b32 m0, s64
	ds_read_b128 v[162:165], v215 offset:16384
	ds_read_b128 v[166:169], v215 offset:17408
	ds_read_b128 v[170:173], v215 offset:18432
	ds_read_b128 v[192:195], v215 offset:19456
	ds_read_b128 v[196:199], v215 offset:20480
	ds_read_b128 v[200:203], v215 offset:21504
	ds_read_b128 v[204:207], v215 offset:22528
	ds_read_b128 v[208:211], v215 offset:23552
	global_load_lds_dwordx4 v[220:221], off
	s_add_i32 m0, s64, 0x2000
	s_add_u32 s64, s34, 0x80000
	v_lshl_add_u64 v[230:231], s[34:35], 0, v[178:179]
	s_addc_u32 s65, s35, 0
	s_add_i32 s66, s66, s41
	global_load_lds_dwordx4 v[230:231], off
	v_lshl_add_u64 v[232:233], s[64:65], 0, v[182:183]
	s_mov_b32 m0, s66
	v_lshl_add_u64 v[234:235], s[36:37], 0, v[180:181]
	global_load_lds_dwordx4 v[232:233], off
	v_lshl_add_u64 v[232:233], s[64:65], 0, v[178:179]
	s_add_i32 m0, s66, 0x2000
	s_nop 0
	global_load_lds_dwordx4 v[232:233], off
	v_lshl_add_u64 v[232:233], s[36:37], 0, v[184:185]
	s_mov_b32 m0, s42
	s_nop 0
	global_load_lds_dwordx4 v[232:233], off
	s_mov_b32 m0, s43
	s_nop 0
	global_load_lds_dwordx4 v[234:235], off
	s_waitcnt vmcnt(8)
	s_waitcnt lgkmcnt(0)
	s_barrier
	s_setprio 1
	v_mfma_f32_16x16x32_bf16 v[62:65], v[66:69], v[162:165], 0
	v_mfma_f32_16x16x32_bf16 v[58:61], v[74:77], v[162:165], 0
	v_mfma_f32_16x16x32_bf16 v[46:49], v[66:69], v[170:173], 0
	v_mfma_f32_16x16x32_bf16 v[42:45], v[74:77], v[170:173], 0
	v_mfma_f32_16x16x32_bf16 v[30:33], v[66:69], v[196:199], 0
	v_mfma_f32_16x16x32_bf16 v[26:29], v[74:77], v[196:199], 0
	v_mfma_f32_16x16x32_bf16 v[14:17], v[66:69], v[204:207], 0
	v_mfma_f32_16x16x32_bf16 v[10:13], v[74:77], v[204:207], 0
	v_mfma_f32_16x16x32_bf16 v[62:65], v[70:73], v[166:169], v[62:65]
	v_mfma_f32_16x16x32_bf16 v[58:61], v[78:81], v[166:169], v[58:61]
	v_mfma_f32_16x16x32_bf16 v[46:49], v[70:73], v[192:195], v[46:49]
	v_mfma_f32_16x16x32_bf16 v[42:45], v[78:81], v[192:195], v[42:45]
	v_mfma_f32_16x16x32_bf16 v[30:33], v[70:73], v[200:203], v[30:33]
	v_mfma_f32_16x16x32_bf16 v[26:29], v[78:81], v[200:203], v[26:29]
	v_mfma_f32_16x16x32_bf16 v[14:17], v[70:73], v[208:211], v[14:17]
	v_mfma_f32_16x16x32_bf16 v[10:13], v[78:81], v[208:211], v[10:13]
	v_mfma_f32_16x16x32_bf16 v[54:57], v[130:133], v[162:165], 0
	v_mfma_f32_16x16x32_bf16 v[50:53], v[146:149], v[162:165], 0
	v_mfma_f32_16x16x32_bf16 v[38:41], v[130:133], v[170:173], 0
	v_mfma_f32_16x16x32_bf16 v[34:37], v[146:149], v[170:173], 0
	v_mfma_f32_16x16x32_bf16 v[22:25], v[130:133], v[196:199], 0
	v_mfma_f32_16x16x32_bf16 v[18:21], v[146:149], v[196:199], 0
	v_mfma_f32_16x16x32_bf16 v[6:9], v[130:133], v[204:207], 0
	v_mfma_f32_16x16x32_bf16 v[2:5], v[146:149], v[204:207], 0
	v_mfma_f32_16x16x32_bf16 v[54:57], v[142:145], v[166:169], v[54:57]
	v_mfma_f32_16x16x32_bf16 v[50:53], v[158:161], v[166:169], v[50:53]
	v_mfma_f32_16x16x32_bf16 v[38:41], v[142:145], v[192:195], v[38:41]
	v_mfma_f32_16x16x32_bf16 v[34:37], v[158:161], v[192:195], v[34:37]
	v_mfma_f32_16x16x32_bf16 v[22:25], v[142:145], v[200:203], v[22:25]
	v_mfma_f32_16x16x32_bf16 v[18:21], v[158:161], v[200:203], v[18:21]
	v_mfma_f32_16x16x32_bf16 v[6:9], v[142:145], v[208:211], v[6:9]
	v_mfma_f32_16x16x32_bf16 v[2:5], v[158:161], v[208:211], v[2:5]
	s_setprio 0
	s_barrier
	s_add_i32 s64, 0, 0x18000
	v_add_u32_e32 v0, s64, v212
	s_add_i32 s65, 0, 0x1c000
	ds_read_b128 v[66:69], v0
	ds_read_b128 v[70:73], v0 offset:1024
	ds_read_b128 v[74:77], v0 offset:2048
	ds_read_b128 v[78:81], v0 offset:3072
	v_add_u32_e32 v0, s65, v212
	ds_read_b128 v[130:133], v0
	ds_read_b128 v[142:145], v0 offset:1024
	ds_read_b128 v[146:149], v0 offset:2048
	ds_read_b128 v[158:161], v0 offset:3072
	s_add_u32 s36, s36, 0x80000
	s_addc_u32 s37, s37, 0
	s_mov_b32 m0, s44
	v_lshl_add_u64 v[236:237], s[36:37], 0, v[184:185]
	ds_read_b128 v[162:165], v215 offset:32768
	ds_read_b128 v[166:169], v215 offset:33792
	ds_read_b128 v[170:173], v215 offset:34816
	ds_read_b128 v[192:195], v215 offset:35840
	ds_read_b128 v[196:199], v215 offset:36864
	ds_read_b128 v[200:203], v215 offset:37888
	ds_read_b128 v[204:207], v215 offset:38912
	ds_read_b128 v[208:211], v215 offset:39936
	global_load_lds_dwordx4 v[236:237], off
	v_lshl_add_u64 v[236:237], s[36:37], 0, v[180:181]
	s_mov_b32 m0, s45
	s_nop 0
	global_load_lds_dwordx4 v[236:237], off
	s_waitcnt vmcnt(8)
	s_waitcnt lgkmcnt(0)
	s_barrier
	s_setprio 1
	v_mfma_f32_16x16x32_bf16 v[154:157], v[66:69], v[162:165], v[154:157]
	v_mfma_f32_16x16x32_bf16 v[150:153], v[74:77], v[162:165], v[150:153]
	v_mfma_f32_16x16x32_bf16 v[138:141], v[66:69], v[170:173], v[138:141]
	v_mfma_f32_16x16x32_bf16 v[134:137], v[74:77], v[170:173], v[134:137]
	v_mfma_f32_16x16x32_bf16 v[110:113], v[66:69], v[196:199], v[110:113]
	v_mfma_f32_16x16x32_bf16 v[106:109], v[74:77], v[196:199], v[106:109]
	v_mfma_f32_16x16x32_bf16 v[94:97], v[66:69], v[204:207], v[94:97]
	v_mfma_f32_16x16x32_bf16 v[90:93], v[74:77], v[204:207], v[90:93]
	v_mfma_f32_16x16x32_bf16 v[154:157], v[70:73], v[166:169], v[154:157]
	v_mfma_f32_16x16x32_bf16 v[150:153], v[78:81], v[166:169], v[150:153]
	v_mfma_f32_16x16x32_bf16 v[138:141], v[70:73], v[192:195], v[138:141]
	v_mfma_f32_16x16x32_bf16 v[134:137], v[78:81], v[192:195], v[134:137]
	v_mfma_f32_16x16x32_bf16 v[110:113], v[70:73], v[200:203], v[110:113]
	v_mfma_f32_16x16x32_bf16 v[106:109], v[78:81], v[200:203], v[106:109]
	v_mfma_f32_16x16x32_bf16 v[94:97], v[70:73], v[208:211], v[94:97]
	v_mfma_f32_16x16x32_bf16 v[90:93], v[78:81], v[208:211], v[90:93]
	v_mfma_f32_16x16x32_bf16 v[126:129], v[130:133], v[162:165], v[126:129]
	v_mfma_f32_16x16x32_bf16 v[114:117], v[146:149], v[162:165], v[114:117]
	v_mfma_f32_16x16x32_bf16 v[122:125], v[130:133], v[170:173], v[122:125]
	v_mfma_f32_16x16x32_bf16 v[118:121], v[146:149], v[170:173], v[118:121]
	v_mfma_f32_16x16x32_bf16 v[102:105], v[130:133], v[196:199], v[102:105]
	v_mfma_f32_16x16x32_bf16 v[98:101], v[146:149], v[196:199], v[98:101]
	v_mfma_f32_16x16x32_bf16 v[86:89], v[130:133], v[204:207], v[86:89]
	v_mfma_f32_16x16x32_bf16 v[82:85], v[146:149], v[204:207], v[82:85]
	v_mfma_f32_16x16x32_bf16 v[126:129], v[142:145], v[166:169], v[126:129]
	v_mfma_f32_16x16x32_bf16 v[114:117], v[158:161], v[166:169], v[114:117]
	v_mfma_f32_16x16x32_bf16 v[122:125], v[142:145], v[192:195], v[122:125]
	v_mfma_f32_16x16x32_bf16 v[118:121], v[158:161], v[192:195], v[118:121]
	v_mfma_f32_16x16x32_bf16 v[102:105], v[142:145], v[200:203], v[102:105]
	v_mfma_f32_16x16x32_bf16 v[98:101], v[158:161], v[200:203], v[98:101]
	v_mfma_f32_16x16x32_bf16 v[86:89], v[142:145], v[208:211], v[86:89]
	v_mfma_f32_16x16x32_bf16 v[82:85], v[158:161], v[208:211], v[82:85]
	s_setprio 0
	s_barrier
	s_add_i32 s36, s64, s41
	v_lshl_add_u64 v[220:221], v[220:221], 0, s[96:97]
	s_mov_b32 m0, s36
	ds_read_b128 v[162:165], v215 offset:49152
	ds_read_b128 v[166:169], v215 offset:50176
	ds_read_b128 v[170:173], v215 offset:51200
	ds_read_b128 v[192:195], v215 offset:52224
	ds_read_b128 v[196:199], v215 offset:53248
	ds_read_b128 v[200:203], v215 offset:54272
	ds_read_b128 v[204:207], v215 offset:55296
	ds_read_b128 v[208:211], v215 offset:56320
	global_load_lds_dwordx4 v[220:221], off
	s_add_i32 m0, s36, 0x2000
	s_add_u32 s34, s34, 0x80080
	v_lshl_add_u64 v[220:221], v[230:231], 0, s[96:97]
	s_addc_u32 s35, s35, 0
	s_add_i32 s36, s65, s41
	global_load_lds_dwordx4 v[220:221], off
	v_lshl_add_u64 v[220:221], s[34:35], 0, v[182:183]
	s_mov_b32 m0, s36
	s_nop 0
	global_load_lds_dwordx4 v[220:221], off
	v_lshl_add_u64 v[220:221], s[34:35], 0, v[178:179]
	s_add_i32 m0, s36, 0x2000
	s_nop 0
	global_load_lds_dwordx4 v[220:221], off
	v_lshl_add_u64 v[220:221], v[232:233], 0, s[96:97]
	s_mov_b32 m0, s56
	s_nop 0
	global_load_lds_dwordx4 v[220:221], off
	v_lshl_add_u64 v[220:221], v[234:235], 0, s[96:97]
	s_mov_b32 m0, s57
	s_nop 0
	global_load_lds_dwordx4 v[220:221], off
	s_waitcnt vmcnt(8)
	s_waitcnt lgkmcnt(0)
	s_barrier
	s_setprio 1
	v_mfma_f32_16x16x32_bf16 v[62:65], v[66:69], v[162:165], v[62:65]
	v_mfma_f32_16x16x32_bf16 v[58:61], v[74:77], v[162:165], v[58:61]
	v_mfma_f32_16x16x32_bf16 v[46:49], v[66:69], v[170:173], v[46:49]
	v_mfma_f32_16x16x32_bf16 v[42:45], v[74:77], v[170:173], v[42:45]
	v_mfma_f32_16x16x32_bf16 v[30:33], v[66:69], v[196:199], v[30:33]
	v_mfma_f32_16x16x32_bf16 v[26:29], v[74:77], v[196:199], v[26:29]
	v_mfma_f32_16x16x32_bf16 v[14:17], v[66:69], v[204:207], v[14:17]
	v_mfma_f32_16x16x32_bf16 v[10:13], v[74:77], v[204:207], v[10:13]
	v_mfma_f32_16x16x32_bf16 v[62:65], v[70:73], v[166:169], v[62:65]
	v_mfma_f32_16x16x32_bf16 v[58:61], v[78:81], v[166:169], v[58:61]
	v_mfma_f32_16x16x32_bf16 v[46:49], v[70:73], v[192:195], v[46:49]
	v_mfma_f32_16x16x32_bf16 v[42:45], v[78:81], v[192:195], v[42:45]
	v_mfma_f32_16x16x32_bf16 v[30:33], v[70:73], v[200:203], v[30:33]
	v_mfma_f32_16x16x32_bf16 v[26:29], v[78:81], v[200:203], v[26:29]
	v_mfma_f32_16x16x32_bf16 v[14:17], v[70:73], v[208:211], v[14:17]
	v_mfma_f32_16x16x32_bf16 v[10:13], v[78:81], v[208:211], v[10:13]
	v_mfma_f32_16x16x32_bf16 v[54:57], v[130:133], v[162:165], v[54:57]
	v_mfma_f32_16x16x32_bf16 v[50:53], v[146:149], v[162:165], v[50:53]
	v_mfma_f32_16x16x32_bf16 v[38:41], v[130:133], v[170:173], v[38:41]
	v_mfma_f32_16x16x32_bf16 v[34:37], v[146:149], v[170:173], v[34:37]
	v_mfma_f32_16x16x32_bf16 v[22:25], v[130:133], v[196:199], v[22:25]
	v_mfma_f32_16x16x32_bf16 v[18:21], v[146:149], v[196:199], v[18:21]
	v_mfma_f32_16x16x32_bf16 v[6:9], v[130:133], v[204:207], v[6:9]
	v_mfma_f32_16x16x32_bf16 v[2:5], v[146:149], v[204:207], v[2:5]
	v_mfma_f32_16x16x32_bf16 v[54:57], v[142:145], v[166:169], v[54:57]
	v_mfma_f32_16x16x32_bf16 v[50:53], v[158:161], v[166:169], v[50:53]
	v_mfma_f32_16x16x32_bf16 v[38:41], v[142:145], v[192:195], v[38:41]
	v_mfma_f32_16x16x32_bf16 v[34:37], v[158:161], v[192:195], v[34:37]
	v_mfma_f32_16x16x32_bf16 v[22:25], v[142:145], v[200:203], v[22:25]
	v_mfma_f32_16x16x32_bf16 v[18:21], v[158:161], v[200:203], v[18:21]
	v_mfma_f32_16x16x32_bf16 v[6:9], v[142:145], v[208:211], v[6:9]
	v_mfma_f32_16x16x32_bf16 v[2:5], v[158:161], v[208:211], v[2:5]
	s_setprio 0
	s_barrier
	s_add_i32 s63, s63, 2
	s_add_u32 s61, s61, 0x100
	s_addc_u32 s62, s62, 0
	s_add_u32 s8, s8, 0x100
	s_addc_u32 s9, s9, 0
	s_cmp_gt_u32 s63, 29

.LBB0_742:
	s_ashr_i32 s31, s30, 31
	s_lshl_b64 s[12:13], s[30:31], 20
	s_add_u32 s34, s2, s12
	s_addc_u32 s35, s52, s13
	s_and_b64 s[12:13], s[10:11], exec
	s_cselect_b32 s31, s35, s39
	s_cselect_b32 s88, s34, s38
	s_ashr_i32 s29, s28, 31
	s_lshl_b64 s[12:13], s[28:29], 20
	s_add_u32 s36, s53, s12
	s_addc_u32 s37, s54, s13
	s_and_b64 s[12:13], s[10:11], exec
	s_cselect_b32 s29, s37, s45
	s_cselect_b32 s90, s36, s44
	s_ashr_i32 s41, s40, 31
	s_lshl_b64 s[12:13], s[40:41], 13
	s_ashr_i32 s41, s40, 5
	s_lshl_b32 s46, s42, 8
	s_lshl_b32 s42, s42, 7
	s_mul_hi_i32 s50, s41, 0xb000
	s_mul_i32 s41, s41, 0xb000
	s_ashr_i32 s47, s46, 31
	s_ashr_i32 s43, s42, 31
	s_add_u32 s41, s69, s41
	v_lshl_add_u64 v[66:67], v[170:171], 0, s[12:13]
	s_addc_u32 s50, s73, s50
	s_lshl_b64 s[12:13], s[46:47], 2
	s_add_u32 s41, s41, s12
	s_addc_u32 s46, s50, s13
	s_lshl_b64 s[12:13], s[42:43], 2
	s_add_u32 s43, s81, s12
	s_addc_u32 s47, s84, s13
	v_mov_b32_e32 v2, s46
	v_mov_b32_e32 v3, s47
	v_lshl_add_u64 v[70:71], v[172:173], 0, s[12:13]
	s_add_u32 s12, s41, 0x200
	v_cndmask_b32_e64 v69, v2, v3, s[14:15]
	v_mov_b32_e32 v2, s41
	v_mov_b32_e32 v3, s43
	s_addc_u32 s13, s46, 0
	v_cndmask_b32_e64 v68, v2, v3, s[14:15]
	s_add_u32 s41, s44, 0x100
	s_addc_u32 s43, s45, 0
	s_mov_b32 s91, -2
	s_cmp_eq_u32 s91, 28
	s_cselect_b64 s[46:47], -1, 0
	s_add_u32 s44, s38, 0x100
	s_addc_u32 s45, s39, 0
	s_and_b64 s[46:47], s[46:47], exec
	s_cselect_b32 s51, s31, s45
	s_cselect_b32 s50, s88, s44
	s_cselect_b32 s47, s29, s43
	s_cselect_b32 s46, s90, s41
	s_add_i32 s93, 0, 0x10000
	s_add_i32 s94, 0, 0x14000
	v_add_u32_e32 v84, s93, v226
	v_add_u32_e32 v88, s94, v226
	ds_read_b128 v[72:75], v84
	ds_read_b128 v[76:79], v84 offset:1024
	ds_read_b128 v[80:83], v84 offset:2048
	ds_read_b128 v[84:87], v84 offset:3072
	ds_read_b128 v[154:157], v88
	ds_read_b128 v[158:161], v88 offset:1024
	ds_read_b128 v[182:185], v88 offset:2048
	ds_read_b128 v[186:189], v88 offset:3072
	v_lshl_add_u64 v[88:89], s[38:39], 0, v[180:181]
	s_add_i32 m0, s56, 0xc000
	ds_read_b128 v[190:193], v230
	ds_read_b128 v[194:197], v230 offset:1024
	ds_read_b128 v[198:201], v230 offset:2048
	ds_read_b128 v[202:205], v230 offset:3072
	ds_read_b128 v[206:209], v230 offset:4096
	ds_read_b128 v[210:213], v230 offset:5120
	ds_read_b128 v[214:217], v230 offset:6144
	ds_read_b128 v[236:239], v230 offset:7168
	global_load_lds_dwordx4 v[88:89], off
	v_lshl_add_u64 v[88:89], s[38:39], 0, v[178:179]
	s_add_i32 m0, s56, 0xe000
	s_nop 0
	global_load_lds_dwordx4 v[88:89], off
	s_waitcnt vmcnt(8)
	s_waitcnt lgkmcnt(0)
	s_barrier
	s_setprio 1
	v_mfma_f32_16x16x32_bf16 v[150:153], v[72:75], v[190:193], 0
	v_mfma_f32_16x16x32_bf16 v[146:149], v[80:83], v[190:193], 0
	v_mfma_f32_16x16x32_bf16 v[118:121], v[72:75], v[198:201], 0
	v_mfma_f32_16x16x32_bf16 v[114:117], v[80:83], v[198:201], 0
	v_mfma_f32_16x16x32_bf16 v[142:145], v[72:75], v[206:209], 0
	v_mfma_f32_16x16x32_bf16 v[134:137], v[80:83], v[206:209], 0
	v_mfma_f32_16x16x32_bf16 v[126:129], v[72:75], v[214:217], 0
	v_mfma_f32_16x16x32_bf16 v[122:125], v[80:83], v[214:217], 0
	v_mfma_f32_16x16x32_bf16 v[150:153], v[76:79], v[194:197], v[150:153]
	v_mfma_f32_16x16x32_bf16 v[146:149], v[84:87], v[194:197], v[146:149]
	v_mfma_f32_16x16x32_bf16 v[118:121], v[76:79], v[202:205], v[118:121]
	v_mfma_f32_16x16x32_bf16 v[114:117], v[84:87], v[202:205], v[114:117]
	v_mfma_f32_16x16x32_bf16 v[142:145], v[76:79], v[210:213], v[142:145]
	v_mfma_f32_16x16x32_bf16 v[134:137], v[84:87], v[210:213], v[134:137]
	v_mfma_f32_16x16x32_bf16 v[126:129], v[76:79], v[236:239], v[126:129]
	v_mfma_f32_16x16x32_bf16 v[122:125], v[84:87], v[236:239], v[122:125]
	v_mfma_f32_16x16x32_bf16 v[138:141], v[154:157], v[190:193], 0
	v_mfma_f32_16x16x32_bf16 v[130:133], v[182:185], v[190:193], 0
	v_mfma_f32_16x16x32_bf16 v[110:113], v[154:157], v[198:201], 0
	v_mfma_f32_16x16x32_bf16 v[106:109], v[182:185], v[198:201], 0
	v_mfma_f32_16x16x32_bf16 v[102:105], v[154:157], v[206:209], 0
	v_mfma_f32_16x16x32_bf16 v[98:101], v[182:185], v[206:209], 0
	v_mfma_f32_16x16x32_bf16 v[94:97], v[154:157], v[214:217], 0
	v_mfma_f32_16x16x32_bf16 v[88:91], v[182:185], v[214:217], 0
	v_mfma_f32_16x16x32_bf16 v[138:141], v[158:161], v[194:197], v[138:141]
	v_mfma_f32_16x16x32_bf16 v[130:133], v[186:189], v[194:197], v[130:133]
	v_mfma_f32_16x16x32_bf16 v[110:113], v[158:161], v[202:205], v[110:113]
	v_mfma_f32_16x16x32_bf16 v[106:109], v[186:189], v[202:205], v[106:109]
	v_mfma_f32_16x16x32_bf16 v[102:105], v[158:161], v[210:213], v[102:105]
	v_mfma_f32_16x16x32_bf16 v[98:101], v[186:189], v[210:213], v[98:101]
	v_mfma_f32_16x16x32_bf16 v[94:97], v[158:161], v[236:239], v[94:97]
	v_mfma_f32_16x16x32_bf16 v[88:91], v[186:189], v[236:239], v[88:91]
	s_setprio 0
	s_barrier
	s_add_i32 s38, s93, s55
	v_lshl_add_u64 v[220:221], s[46:47], 0, v[166:167]
	s_mov_b32 m0, s38
	ds_read_b128 v[190:193], v230 offset:16384
	ds_read_b128 v[194:197], v230 offset:17408
	ds_read_b128 v[198:201], v230 offset:18432
	ds_read_b128 v[202:205], v230 offset:19456
	ds_read_b128 v[206:209], v230 offset:20480
	ds_read_b128 v[210:213], v230 offset:21504
	ds_read_b128 v[214:217], v230 offset:22528
	ds_read_b128 v[236:239], v230 offset:23552
	global_load_lds_dwordx4 v[220:221], off
	s_add_i32 m0, s38, 0x2000
	s_add_u32 s38, s46, 0x80000
	v_lshl_add_u64 v[240:241], s[46:47], 0, v[162:163]
	s_addc_u32 s39, s47, 0
	s_add_i32 s93, s94, s55
	global_load_lds_dwordx4 v[240:241], off
	v_lshl_add_u64 v[92:93], s[38:39], 0, v[166:167]
	s_mov_b32 m0, s93
	v_lshl_add_u64 v[242:243], s[50:51], 0, v[168:169]
	global_load_lds_dwordx4 v[92:93], off
	v_lshl_add_u64 v[92:93], s[38:39], 0, v[162:163]
	s_add_i32 m0, s93, 0x2000
	v_lshl_add_u64 v[244:245], s[50:51], 0, v[164:165]
	global_load_lds_dwordx4 v[92:93], off
	s_mov_b32 m0, s56
	s_nop 0
	global_load_lds_dwordx4 v[242:243], off
	s_mov_b32 m0, s57
	s_nop 0
	global_load_lds_dwordx4 v[244:245], off
	s_waitcnt vmcnt(8)
	s_waitcnt lgkmcnt(0)
	s_barrier
	s_setprio 1
	v_mfma_f32_16x16x32_bf16 v[62:65], v[72:75], v[190:193], 0
	v_mfma_f32_16x16x32_bf16 v[58:61], v[80:83], v[190:193], 0
	v_mfma_f32_16x16x32_bf16 v[54:57], v[72:75], v[198:201], 0
	v_mfma_f32_16x16x32_bf16 v[46:49], v[80:83], v[198:201], 0
	v_mfma_f32_16x16x32_bf16 v[38:41], v[72:75], v[206:209], 0
	v_mfma_f32_16x16x32_bf16 v[30:33], v[80:83], v[206:209], 0
	v_mfma_f32_16x16x32_bf16 v[22:25], v[72:75], v[214:217], 0
	v_mfma_f32_16x16x32_bf16 v[14:17], v[80:83], v[214:217], 0
	v_mfma_f32_16x16x32_bf16 v[62:65], v[76:79], v[194:197], v[62:65]
	v_mfma_f32_16x16x32_bf16 v[58:61], v[84:87], v[194:197], v[58:61]
	v_mfma_f32_16x16x32_bf16 v[54:57], v[76:79], v[202:205], v[54:57]
	v_mfma_f32_16x16x32_bf16 v[46:49], v[84:87], v[202:205], v[46:49]
	v_mfma_f32_16x16x32_bf16 v[38:41], v[76:79], v[210:213], v[38:41]
	v_mfma_f32_16x16x32_bf16 v[30:33], v[84:87], v[210:213], v[30:33]
	v_mfma_f32_16x16x32_bf16 v[22:25], v[76:79], v[236:239], v[22:25]
	v_mfma_f32_16x16x32_bf16 v[14:17], v[84:87], v[236:239], v[14:17]
	v_mfma_f32_16x16x32_bf16 v[50:53], v[154:157], v[190:193], 0
	v_mfma_f32_16x16x32_bf16 v[42:45], v[182:185], v[190:193], 0
	v_mfma_f32_16x16x32_bf16 v[34:37], v[154:157], v[198:201], 0
	v_mfma_f32_16x16x32_bf16 v[26:29], v[182:185], v[198:201], 0
	v_mfma_f32_16x16x32_bf16 v[18:21], v[154:157], v[206:209], 0
	v_mfma_f32_16x16x32_bf16 v[10:13], v[182:185], v[206:209], 0
	v_mfma_f32_16x16x32_bf16 v[6:9], v[154:157], v[214:217], 0
	v_mfma_f32_16x16x32_bf16 v[2:5], v[182:185], v[214:217], 0
	v_mfma_f32_16x16x32_bf16 v[50:53], v[158:161], v[194:197], v[50:53]
	v_mfma_f32_16x16x32_bf16 v[42:45], v[186:189], v[194:197], v[42:45]
	v_mfma_f32_16x16x32_bf16 v[34:37], v[158:161], v[202:205], v[34:37]
	v_mfma_f32_16x16x32_bf16 v[26:29], v[186:189], v[202:205], v[26:29]
	v_mfma_f32_16x16x32_bf16 v[18:21], v[158:161], v[210:213], v[18:21]
	v_mfma_f32_16x16x32_bf16 v[10:13], v[186:189], v[210:213], v[10:13]
	v_mfma_f32_16x16x32_bf16 v[6:9], v[158:161], v[236:239], v[6:9]
	v_mfma_f32_16x16x32_bf16 v[2:5], v[186:189], v[236:239], v[2:5]
	s_setprio 0
	s_barrier
	s_add_i32 s93, 0, 0x18000
	s_add_i32 s94, 0, 0x1c000
	v_add_u32_e32 v84, s93, v226
	v_add_u32_e32 v92, s94, v226
	ds_read_b128 v[72:75], v84
	ds_read_b128 v[76:79], v84 offset:1024
	ds_read_b128 v[80:83], v84 offset:2048
	ds_read_b128 v[84:87], v84 offset:3072
	ds_read_b128 v[154:157], v92
	ds_read_b128 v[158:161], v92 offset:1024
	ds_read_b128 v[182:185], v92 offset:2048
	ds_read_b128 v[186:189], v92 offset:3072
	s_add_u32 s38, s50, 0x80000
	s_addc_u32 s39, s51, 0
	s_mov_b32 m0, s60
	v_lshl_add_u64 v[92:93], s[38:39], 0, v[168:169]
	ds_read_b128 v[190:193], v230 offset:32768
	ds_read_b128 v[194:197], v230 offset:33792
	ds_read_b128 v[198:201], v230 offset:34816
	ds_read_b128 v[202:205], v230 offset:35840
	ds_read_b128 v[206:209], v230 offset:36864
	ds_read_b128 v[210:213], v230 offset:37888
	ds_read_b128 v[214:217], v230 offset:38912
	ds_read_b128 v[236:239], v230 offset:39936
	global_load_lds_dwordx4 v[92:93], off
	v_lshl_add_u64 v[92:93], s[38:39], 0, v[164:165]
	s_mov_b32 m0, s61
	s_nop 0
	global_load_lds_dwordx4 v[92:93], off
	s_waitcnt vmcnt(8)
	s_waitcnt lgkmcnt(0)
	s_barrier
	s_setprio 1
	v_mfma_f32_16x16x32_bf16 v[150:153], v[72:75], v[190:193], v[150:153]
	v_mfma_f32_16x16x32_bf16 v[146:149], v[80:83], v[190:193], v[146:149]
	v_mfma_f32_16x16x32_bf16 v[118:121], v[72:75], v[198:201], v[118:121]
	v_mfma_f32_16x16x32_bf16 v[114:117], v[80:83], v[198:201], v[114:117]
	v_mfma_f32_16x16x32_bf16 v[142:145], v[72:75], v[206:209], v[142:145]
	v_mfma_f32_16x16x32_bf16 v[134:137], v[80:83], v[206:209], v[134:137]
	v_mfma_f32_16x16x32_bf16 v[126:129], v[72:75], v[214:217], v[126:129]
	v_mfma_f32_16x16x32_bf16 v[122:125], v[80:83], v[214:217], v[122:125]
	v_mfma_f32_16x16x32_bf16 v[150:153], v[76:79], v[194:197], v[150:153]
	v_mfma_f32_16x16x32_bf16 v[146:149], v[84:87], v[194:197], v[146:149]
	v_mfma_f32_16x16x32_bf16 v[118:121], v[76:79], v[202:205], v[118:121]
	v_mfma_f32_16x16x32_bf16 v[114:117], v[84:87], v[202:205], v[114:117]
	v_mfma_f32_16x16x32_bf16 v[142:145], v[76:79], v[210:213], v[142:145]
	v_mfma_f32_16x16x32_bf16 v[134:137], v[84:87], v[210:213], v[134:137]
	v_mfma_f32_16x16x32_bf16 v[126:129], v[76:79], v[236:239], v[126:129]
	v_mfma_f32_16x16x32_bf16 v[122:125], v[84:87], v[236:239], v[122:125]
	v_mfma_f32_16x16x32_bf16 v[138:141], v[154:157], v[190:193], v[138:141]
	v_mfma_f32_16x16x32_bf16 v[130:133], v[182:185], v[190:193], v[130:133]
	v_mfma_f32_16x16x32_bf16 v[110:113], v[154:157], v[198:201], v[110:113]
	v_mfma_f32_16x16x32_bf16 v[106:109], v[182:185], v[198:201], v[106:109]
	v_mfma_f32_16x16x32_bf16 v[102:105], v[154:157], v[206:209], v[102:105]
	v_mfma_f32_16x16x32_bf16 v[98:101], v[182:185], v[206:209], v[98:101]
	v_mfma_f32_16x16x32_bf16 v[92:95], v[154:157], v[214:217], v[94:97]
	v_mfma_f32_16x16x32_bf16 v[88:91], v[182:185], v[214:217], v[88:91]
	v_mfma_f32_16x16x32_bf16 v[138:141], v[158:161], v[194:197], v[138:141]
	v_mfma_f32_16x16x32_bf16 v[130:133], v[186:189], v[194:197], v[130:133]
	v_mfma_f32_16x16x32_bf16 v[110:113], v[158:161], v[202:205], v[110:113]
	v_mfma_f32_16x16x32_bf16 v[106:109], v[186:189], v[202:205], v[106:109]
	v_mfma_f32_16x16x32_bf16 v[102:105], v[158:161], v[210:213], v[102:105]
	v_mfma_f32_16x16x32_bf16 v[98:101], v[186:189], v[210:213], v[98:101]
	v_mfma_f32_16x16x32_bf16 v[94:97], v[158:161], v[236:239], v[92:95]
	v_mfma_f32_16x16x32_bf16 v[90:93], v[186:189], v[236:239], v[88:91]
	s_setprio 0
	s_barrier
	s_add_i32 s38, s93, s55
	v_lshl_add_u64 v[88:89], v[220:221], 0, s[96:97]
	s_mov_b32 m0, s38
	ds_read_b128 v[190:193], v230 offset:49152
	ds_read_b128 v[194:197], v230 offset:50176
	ds_read_b128 v[198:201], v230 offset:51200
	ds_read_b128 v[202:205], v230 offset:52224
	ds_read_b128 v[206:209], v230 offset:53248
	ds_read_b128 v[210:213], v230 offset:54272
	ds_read_b128 v[214:217], v230 offset:55296
	ds_read_b128 v[236:239], v230 offset:56320
	global_load_lds_dwordx4 v[88:89], off
	s_add_i32 m0, s38, 0x2000
	s_add_u32 s38, s46, 0x80080
	v_lshl_add_u64 v[88:89], v[240:241], 0, s[96:97]
	s_addc_u32 s39, s47, 0
	s_add_i32 s46, s94, s55
	global_load_lds_dwordx4 v[88:89], off
	v_lshl_add_u64 v[88:89], s[38:39], 0, v[166:167]
	s_mov_b32 m0, s46
	s_nop 0
	global_load_lds_dwordx4 v[88:89], off
	v_lshl_add_u64 v[88:89], s[38:39], 0, v[162:163]
	s_add_i32 m0, s46, 0x2000
	s_nop 0
	global_load_lds_dwordx4 v[88:89], off
	v_lshl_add_u64 v[88:89], v[242:243], 0, s[96:97]
	s_mov_b32 m0, s75
	s_nop 0
	global_load_lds_dwordx4 v[88:89], off
	v_lshl_add_u64 v[88:89], v[244:245], 0, s[96:97]
	s_mov_b32 m0, s76
	s_nop 0
	global_load_lds_dwordx4 v[88:89], off
	s_waitcnt vmcnt(8)
	s_waitcnt lgkmcnt(0)
	s_barrier
	s_setprio 1
	v_mfma_f32_16x16x32_bf16 v[62:65], v[72:75], v[190:193], v[62:65]
	v_mfma_f32_16x16x32_bf16 v[58:61], v[80:83], v[190:193], v[58:61]
	v_mfma_f32_16x16x32_bf16 v[54:57], v[72:75], v[198:201], v[54:57]
	v_mfma_f32_16x16x32_bf16 v[46:49], v[80:83], v[198:201], v[46:49]
	v_mfma_f32_16x16x32_bf16 v[38:41], v[72:75], v[206:209], v[38:41]
	v_mfma_f32_16x16x32_bf16 v[30:33], v[80:83], v[206:209], v[30:33]
	v_mfma_f32_16x16x32_bf16 v[22:25], v[72:75], v[214:217], v[22:25]
	v_mfma_f32_16x16x32_bf16 v[14:17], v[80:83], v[214:217], v[14:17]
	v_mfma_f32_16x16x32_bf16 v[62:65], v[76:79], v[194:197], v[62:65]
	v_mfma_f32_16x16x32_bf16 v[58:61], v[84:87], v[194:197], v[58:61]
	v_mfma_f32_16x16x32_bf16 v[54:57], v[76:79], v[202:205], v[54:57]
	v_mfma_f32_16x16x32_bf16 v[46:49], v[84:87], v[202:205], v[46:49]
	v_mfma_f32_16x16x32_bf16 v[38:41], v[76:79], v[210:213], v[38:41]
	v_mfma_f32_16x16x32_bf16 v[30:33], v[84:87], v[210:213], v[30:33]
	v_mfma_f32_16x16x32_bf16 v[22:25], v[76:79], v[236:239], v[22:25]
	v_mfma_f32_16x16x32_bf16 v[14:17], v[84:87], v[236:239], v[14:17]
	v_mfma_f32_16x16x32_bf16 v[50:53], v[154:157], v[190:193], v[50:53]
	v_mfma_f32_16x16x32_bf16 v[42:45], v[182:185], v[190:193], v[42:45]
	v_mfma_f32_16x16x32_bf16 v[34:37], v[154:157], v[198:201], v[34:37]
	v_mfma_f32_16x16x32_bf16 v[26:29], v[182:185], v[198:201], v[26:29]
	v_mfma_f32_16x16x32_bf16 v[18:21], v[154:157], v[206:209], v[18:21]
	v_mfma_f32_16x16x32_bf16 v[10:13], v[182:185], v[206:209], v[10:13]
	v_mfma_f32_16x16x32_bf16 v[6:9], v[154:157], v[214:217], v[6:9]
	v_mfma_f32_16x16x32_bf16 v[2:5], v[182:185], v[214:217], v[2:5]
	v_mfma_f32_16x16x32_bf16 v[50:53], v[158:161], v[194:197], v[50:53]
	v_mfma_f32_16x16x32_bf16 v[42:45], v[186:189], v[194:197], v[42:45]
	v_mfma_f32_16x16x32_bf16 v[34:37], v[158:161], v[202:205], v[34:37]
	v_mfma_f32_16x16x32_bf16 v[26:29], v[186:189], v[202:205], v[26:29]
	v_mfma_f32_16x16x32_bf16 v[18:21], v[158:161], v[210:213], v[18:21]
	v_mfma_f32_16x16x32_bf16 v[10:13], v[186:189], v[210:213], v[10:13]
	v_mfma_f32_16x16x32_bf16 v[6:9], v[158:161], v[236:239], v[6:9]
	v_mfma_f32_16x16x32_bf16 v[2:5], v[186:189], v[236:239], v[2:5]
	s_setprio 0
	s_barrier
	s_add_i32 s91, s91, 2
	s_add_u32 s41, s41, 0x100
	s_addc_u32 s43, s43, 0
	s_cmp_gt_u32 s91, 29
	s_mov_b64 s[38:39], s[44:45]
	s_cbranch_scc1 .LBB0_755
	s_branch .LBB0_745

.LBB0_904:
	s_add_u32 s19, s28, 0x100
	s_addc_u32 s21, s29, 0
	s_mov_b32 s60, -2
	s_add_u32 s8, s26, 0x100
	s_addc_u32 s9, s27, 0
	s_add_i32 s61, 0, 0x10000
	s_cmpk_eq_i32 s60, 0x54
	s_cselect_b32 s31, s23, s9
	s_cselect_b32 s30, s22, s8
	v_add_u32_e32 v0, s61, v212
	s_cselect_b32 s29, s25, s21
	s_cselect_b32 s28, s24, s19
	s_add_i32 s62, 0, 0x14000
	ds_read_b128 v[66:69], v0
	ds_read_b128 v[70:73], v0 offset:1024
	ds_read_b128 v[74:77], v0 offset:2048
	ds_read_b128 v[78:81], v0 offset:3072
	v_add_u32_e32 v0, s62, v212
	ds_read_b128 v[130:133], v0
	ds_read_b128 v[142:145], v0 offset:1024
	ds_read_b128 v[146:149], v0 offset:2048
	ds_read_b128 v[158:161], v0 offset:3072
	v_lshl_add_u64 v[220:221], s[26:27], 0, v[190:191]
	s_add_i32 m0, s39, 0xc000
	ds_read_b128 v[162:165], v215
	ds_read_b128 v[166:169], v215 offset:1024
	ds_read_b128 v[170:173], v215 offset:2048
	ds_read_b128 v[192:195], v215 offset:3072
	ds_read_b128 v[196:199], v215 offset:4096
	ds_read_b128 v[200:203], v215 offset:5120
	ds_read_b128 v[204:207], v215 offset:6144
	ds_read_b128 v[208:211], v215 offset:7168
	global_load_lds_dwordx4 v[220:221], off
	v_lshl_add_u64 v[220:221], s[26:27], 0, v[188:189]
	s_add_i32 m0, s39, 0xe000
	s_nop 0
	global_load_lds_dwordx4 v[220:221], off
	s_waitcnt vmcnt(8)
	s_waitcnt lgkmcnt(0)
	s_barrier
	s_setprio 1
	v_mfma_f32_16x16x32_bf16 v[154:157], v[66:69], v[162:165], 0
	v_mfma_f32_16x16x32_bf16 v[150:153], v[74:77], v[162:165], 0
	v_mfma_f32_16x16x32_bf16 v[138:141], v[66:69], v[170:173], 0
	v_mfma_f32_16x16x32_bf16 v[134:137], v[74:77], v[170:173], 0
	v_mfma_f32_16x16x32_bf16 v[110:113], v[66:69], v[196:199], 0
	v_mfma_f32_16x16x32_bf16 v[106:109], v[74:77], v[196:199], 0
	v_mfma_f32_16x16x32_bf16 v[94:97], v[66:69], v[204:207], 0
	v_mfma_f32_16x16x32_bf16 v[90:93], v[74:77], v[204:207], 0
	v_mfma_f32_16x16x32_bf16 v[154:157], v[70:73], v[166:169], v[154:157]
	v_mfma_f32_16x16x32_bf16 v[150:153], v[78:81], v[166:169], v[150:153]
	v_mfma_f32_16x16x32_bf16 v[138:141], v[70:73], v[192:195], v[138:141]
	v_mfma_f32_16x16x32_bf16 v[134:137], v[78:81], v[192:195], v[134:137]
	v_mfma_f32_16x16x32_bf16 v[110:113], v[70:73], v[200:203], v[110:113]
	v_mfma_f32_16x16x32_bf16 v[106:109], v[78:81], v[200:203], v[106:109]
	v_mfma_f32_16x16x32_bf16 v[94:97], v[70:73], v[208:211], v[94:97]
	v_mfma_f32_16x16x32_bf16 v[90:93], v[78:81], v[208:211], v[90:93]
	v_mfma_f32_16x16x32_bf16 v[126:129], v[130:133], v[162:165], 0
	v_mfma_f32_16x16x32_bf16 v[114:117], v[146:149], v[162:165], 0
	v_mfma_f32_16x16x32_bf16 v[122:125], v[130:133], v[170:173], 0
	v_mfma_f32_16x16x32_bf16 v[118:121], v[146:149], v[170:173], 0
	v_mfma_f32_16x16x32_bf16 v[102:105], v[130:133], v[196:199], 0
	v_mfma_f32_16x16x32_bf16 v[98:101], v[146:149], v[196:199], 0
	v_mfma_f32_16x16x32_bf16 v[86:89], v[130:133], v[204:207], 0
	v_mfma_f32_16x16x32_bf16 v[82:85], v[146:149], v[204:207], 0
	v_mfma_f32_16x16x32_bf16 v[126:129], v[142:145], v[166:169], v[126:129]
	v_mfma_f32_16x16x32_bf16 v[114:117], v[158:161], v[166:169], v[114:117]
	v_mfma_f32_16x16x32_bf16 v[122:125], v[142:145], v[192:195], v[122:125]
	v_mfma_f32_16x16x32_bf16 v[118:121], v[158:161], v[192:195], v[118:121]
	v_mfma_f32_16x16x32_bf16 v[102:105], v[142:145], v[200:203], v[102:105]
	v_mfma_f32_16x16x32_bf16 v[98:101], v[158:161], v[200:203], v[98:101]
	v_mfma_f32_16x16x32_bf16 v[86:89], v[142:145], v[208:211], v[86:89]
	v_mfma_f32_16x16x32_bf16 v[82:85], v[158:161], v[208:211], v[82:85]
	s_setprio 0
	s_barrier
	s_add_i32 s26, s61, s38
	v_lshl_add_u64 v[220:221], s[28:29], 0, v[182:183]
	s_mov_b32 m0, s26
	ds_read_b128 v[162:165], v215 offset:16384
	ds_read_b128 v[166:169], v215 offset:17408
	ds_read_b128 v[170:173], v215 offset:18432
	ds_read_b128 v[192:195], v215 offset:19456
	ds_read_b128 v[196:199], v215 offset:20480
	ds_read_b128 v[200:203], v215 offset:21504
	ds_read_b128 v[204:207], v215 offset:22528
	ds_read_b128 v[208:211], v215 offset:23552
	global_load_lds_dwordx4 v[220:221], off
	s_add_i32 m0, s26, 0x2000
	s_add_u32 s26, s28, 0x160000
	v_lshl_add_u64 v[230:231], s[28:29], 0, v[178:179]
	s_addc_u32 s27, s29, 0
	s_add_i32 s61, s62, s38
	global_load_lds_dwordx4 v[230:231], off
	v_lshl_add_u64 v[232:233], s[26:27], 0, v[182:183]
	s_mov_b32 m0, s61
	v_lshl_add_u64 v[234:235], s[30:31], 0, v[180:181]
	global_load_lds_dwordx4 v[232:233], off
	v_lshl_add_u64 v[232:233], s[26:27], 0, v[178:179]
	s_add_i32 m0, s61, 0x2000
	s_nop 0
	global_load_lds_dwordx4 v[232:233], off
	v_lshl_add_u64 v[232:233], s[30:31], 0, v[184:185]
	s_mov_b32 m0, s39
	s_nop 0
	global_load_lds_dwordx4 v[232:233], off
	s_mov_b32 m0, s40
	s_nop 0
	global_load_lds_dwordx4 v[234:235], off
	s_waitcnt vmcnt(8)
	s_waitcnt lgkmcnt(0)
	s_barrier
	s_setprio 1
	v_mfma_f32_16x16x32_bf16 v[62:65], v[66:69], v[162:165], 0
	v_mfma_f32_16x16x32_bf16 v[58:61], v[74:77], v[162:165], 0
	v_mfma_f32_16x16x32_bf16 v[46:49], v[66:69], v[170:173], 0
	v_mfma_f32_16x16x32_bf16 v[42:45], v[74:77], v[170:173], 0
	v_mfma_f32_16x16x32_bf16 v[30:33], v[66:69], v[196:199], 0
	v_mfma_f32_16x16x32_bf16 v[26:29], v[74:77], v[196:199], 0
	v_mfma_f32_16x16x32_bf16 v[14:17], v[66:69], v[204:207], 0
	v_mfma_f32_16x16x32_bf16 v[10:13], v[74:77], v[204:207], 0
	v_mfma_f32_16x16x32_bf16 v[62:65], v[70:73], v[166:169], v[62:65]
	v_mfma_f32_16x16x32_bf16 v[58:61], v[78:81], v[166:169], v[58:61]
	v_mfma_f32_16x16x32_bf16 v[46:49], v[70:73], v[192:195], v[46:49]
	v_mfma_f32_16x16x32_bf16 v[42:45], v[78:81], v[192:195], v[42:45]
	v_mfma_f32_16x16x32_bf16 v[30:33], v[70:73], v[200:203], v[30:33]
	v_mfma_f32_16x16x32_bf16 v[26:29], v[78:81], v[200:203], v[26:29]
	v_mfma_f32_16x16x32_bf16 v[14:17], v[70:73], v[208:211], v[14:17]
	v_mfma_f32_16x16x32_bf16 v[10:13], v[78:81], v[208:211], v[10:13]
	v_mfma_f32_16x16x32_bf16 v[54:57], v[130:133], v[162:165], 0
	v_mfma_f32_16x16x32_bf16 v[50:53], v[146:149], v[162:165], 0
	v_mfma_f32_16x16x32_bf16 v[38:41], v[130:133], v[170:173], 0
	v_mfma_f32_16x16x32_bf16 v[34:37], v[146:149], v[170:173], 0
	v_mfma_f32_16x16x32_bf16 v[22:25], v[130:133], v[196:199], 0
	v_mfma_f32_16x16x32_bf16 v[18:21], v[146:149], v[196:199], 0
	v_mfma_f32_16x16x32_bf16 v[6:9], v[130:133], v[204:207], 0
	v_mfma_f32_16x16x32_bf16 v[2:5], v[146:149], v[204:207], 0
	v_mfma_f32_16x16x32_bf16 v[54:57], v[142:145], v[166:169], v[54:57]
	v_mfma_f32_16x16x32_bf16 v[50:53], v[158:161], v[166:169], v[50:53]
	v_mfma_f32_16x16x32_bf16 v[38:41], v[142:145], v[192:195], v[38:41]
	v_mfma_f32_16x16x32_bf16 v[34:37], v[158:161], v[192:195], v[34:37]
	v_mfma_f32_16x16x32_bf16 v[22:25], v[142:145], v[200:203], v[22:25]
	v_mfma_f32_16x16x32_bf16 v[18:21], v[158:161], v[200:203], v[18:21]
	v_mfma_f32_16x16x32_bf16 v[6:9], v[142:145], v[208:211], v[6:9]
	v_mfma_f32_16x16x32_bf16 v[2:5], v[158:161], v[208:211], v[2:5]
	s_setprio 0
	s_barrier
	s_add_i32 s61, 0, 0x18000
	v_add_u32_e32 v0, s61, v212
	s_add_i32 s62, 0, 0x1c000
	ds_read_b128 v[66:69], v0
	ds_read_b128 v[70:73], v0 offset:1024
	ds_read_b128 v[74:77], v0 offset:2048
	ds_read_b128 v[78:81], v0 offset:3072
	v_add_u32_e32 v0, s62, v212
	ds_read_b128 v[130:133], v0
	ds_read_b128 v[142:145], v0 offset:1024
	ds_read_b128 v[146:149], v0 offset:2048
	ds_read_b128 v[158:161], v0 offset:3072
	s_add_u32 s26, s30, 0x160000
	s_addc_u32 s27, s31, 0
	s_mov_b32 m0, s41
	v_lshl_add_u64 v[236:237], s[26:27], 0, v[184:185]
	ds_read_b128 v[162:165], v215 offset:32768
	ds_read_b128 v[166:169], v215 offset:33792
	ds_read_b128 v[170:173], v215 offset:34816
	ds_read_b128 v[192:195], v215 offset:35840
	ds_read_b128 v[196:199], v215 offset:36864
	ds_read_b128 v[200:203], v215 offset:37888
	ds_read_b128 v[204:207], v215 offset:38912
	ds_read_b128 v[208:211], v215 offset:39936
	global_load_lds_dwordx4 v[236:237], off
	v_lshl_add_u64 v[236:237], s[26:27], 0, v[180:181]
	s_mov_b32 m0, s42
	s_nop 0
	global_load_lds_dwordx4 v[236:237], off
	s_waitcnt vmcnt(8)
	s_waitcnt lgkmcnt(0)
	s_barrier
	s_setprio 1
	v_mfma_f32_16x16x32_bf16 v[154:157], v[66:69], v[162:165], v[154:157]
	v_mfma_f32_16x16x32_bf16 v[150:153], v[74:77], v[162:165], v[150:153]
	v_mfma_f32_16x16x32_bf16 v[138:141], v[66:69], v[170:173], v[138:141]
	v_mfma_f32_16x16x32_bf16 v[134:137], v[74:77], v[170:173], v[134:137]
	v_mfma_f32_16x16x32_bf16 v[110:113], v[66:69], v[196:199], v[110:113]
	v_mfma_f32_16x16x32_bf16 v[106:109], v[74:77], v[196:199], v[106:109]
	v_mfma_f32_16x16x32_bf16 v[94:97], v[66:69], v[204:207], v[94:97]
	v_mfma_f32_16x16x32_bf16 v[90:93], v[74:77], v[204:207], v[90:93]
	v_mfma_f32_16x16x32_bf16 v[154:157], v[70:73], v[166:169], v[154:157]
	v_mfma_f32_16x16x32_bf16 v[150:153], v[78:81], v[166:169], v[150:153]
	v_mfma_f32_16x16x32_bf16 v[138:141], v[70:73], v[192:195], v[138:141]
	v_mfma_f32_16x16x32_bf16 v[134:137], v[78:81], v[192:195], v[134:137]
	v_mfma_f32_16x16x32_bf16 v[110:113], v[70:73], v[200:203], v[110:113]
	v_mfma_f32_16x16x32_bf16 v[106:109], v[78:81], v[200:203], v[106:109]
	v_mfma_f32_16x16x32_bf16 v[94:97], v[70:73], v[208:211], v[94:97]
	v_mfma_f32_16x16x32_bf16 v[90:93], v[78:81], v[208:211], v[90:93]
	v_mfma_f32_16x16x32_bf16 v[126:129], v[130:133], v[162:165], v[126:129]
	v_mfma_f32_16x16x32_bf16 v[114:117], v[146:149], v[162:165], v[114:117]
	v_mfma_f32_16x16x32_bf16 v[122:125], v[130:133], v[170:173], v[122:125]
	v_mfma_f32_16x16x32_bf16 v[118:121], v[146:149], v[170:173], v[118:121]
	v_mfma_f32_16x16x32_bf16 v[102:105], v[130:133], v[196:199], v[102:105]
	v_mfma_f32_16x16x32_bf16 v[98:101], v[146:149], v[196:199], v[98:101]
	v_mfma_f32_16x16x32_bf16 v[86:89], v[130:133], v[204:207], v[86:89]
	v_mfma_f32_16x16x32_bf16 v[82:85], v[146:149], v[204:207], v[82:85]
	v_mfma_f32_16x16x32_bf16 v[126:129], v[142:145], v[166:169], v[126:129]
	v_mfma_f32_16x16x32_bf16 v[114:117], v[158:161], v[166:169], v[114:117]
	v_mfma_f32_16x16x32_bf16 v[122:125], v[142:145], v[192:195], v[122:125]
	v_mfma_f32_16x16x32_bf16 v[118:121], v[158:161], v[192:195], v[118:121]
	v_mfma_f32_16x16x32_bf16 v[102:105], v[142:145], v[200:203], v[102:105]
	v_mfma_f32_16x16x32_bf16 v[98:101], v[158:161], v[200:203], v[98:101]
	v_mfma_f32_16x16x32_bf16 v[86:89], v[142:145], v[208:211], v[86:89]
	v_mfma_f32_16x16x32_bf16 v[82:85], v[158:161], v[208:211], v[82:85]
	s_setprio 0
	s_barrier
	s_add_i32 s26, s61, s38
	v_lshl_add_u64 v[220:221], v[220:221], 0, s[96:97]
	s_mov_b32 m0, s26
	ds_read_b128 v[162:165], v215 offset:49152
	ds_read_b128 v[166:169], v215 offset:50176
	ds_read_b128 v[170:173], v215 offset:51200
	ds_read_b128 v[192:195], v215 offset:52224
	ds_read_b128 v[196:199], v215 offset:53248
	ds_read_b128 v[200:203], v215 offset:54272
	ds_read_b128 v[204:207], v215 offset:55296
	ds_read_b128 v[208:211], v215 offset:56320
	global_load_lds_dwordx4 v[220:221], off
	s_add_i32 m0, s26, 0x2000
	s_add_u32 s26, s28, 0x160080
	v_lshl_add_u64 v[220:221], v[230:231], 0, s[96:97]
	s_addc_u32 s27, s29, 0
	s_add_i32 s28, s62, s38
	global_load_lds_dwordx4 v[220:221], off
	v_lshl_add_u64 v[220:221], s[26:27], 0, v[182:183]
	s_mov_b32 m0, s28
	s_nop 0
	global_load_lds_dwordx4 v[220:221], off
	v_lshl_add_u64 v[220:221], s[26:27], 0, v[178:179]
	s_add_i32 m0, s28, 0x2000
	s_nop 0
	global_load_lds_dwordx4 v[220:221], off
	v_lshl_add_u64 v[220:221], v[232:233], 0, s[96:97]
	s_mov_b32 m0, s54
	s_nop 0
	global_load_lds_dwordx4 v[220:221], off
	v_lshl_add_u64 v[220:221], v[234:235], 0, s[96:97]
	s_mov_b32 m0, s55
	s_nop 0
	global_load_lds_dwordx4 v[220:221], off
	s_waitcnt vmcnt(8)
	s_waitcnt lgkmcnt(0)
	s_barrier
	s_setprio 1
	v_mfma_f32_16x16x32_bf16 v[62:65], v[66:69], v[162:165], v[62:65]
	v_mfma_f32_16x16x32_bf16 v[58:61], v[74:77], v[162:165], v[58:61]
	v_mfma_f32_16x16x32_bf16 v[46:49], v[66:69], v[170:173], v[46:49]
	v_mfma_f32_16x16x32_bf16 v[42:45], v[74:77], v[170:173], v[42:45]
	v_mfma_f32_16x16x32_bf16 v[30:33], v[66:69], v[196:199], v[30:33]
	v_mfma_f32_16x16x32_bf16 v[26:29], v[74:77], v[196:199], v[26:29]
	v_mfma_f32_16x16x32_bf16 v[14:17], v[66:69], v[204:207], v[14:17]
	v_mfma_f32_16x16x32_bf16 v[10:13], v[74:77], v[204:207], v[10:13]
	v_mfma_f32_16x16x32_bf16 v[62:65], v[70:73], v[166:169], v[62:65]
	v_mfma_f32_16x16x32_bf16 v[58:61], v[78:81], v[166:169], v[58:61]
	v_mfma_f32_16x16x32_bf16 v[46:49], v[70:73], v[192:195], v[46:49]
	v_mfma_f32_16x16x32_bf16 v[42:45], v[78:81], v[192:195], v[42:45]
	v_mfma_f32_16x16x32_bf16 v[30:33], v[70:73], v[200:203], v[30:33]
	v_mfma_f32_16x16x32_bf16 v[26:29], v[78:81], v[200:203], v[26:29]
	v_mfma_f32_16x16x32_bf16 v[14:17], v[70:73], v[208:211], v[14:17]
	v_mfma_f32_16x16x32_bf16 v[10:13], v[78:81], v[208:211], v[10:13]
	v_mfma_f32_16x16x32_bf16 v[54:57], v[130:133], v[162:165], v[54:57]
	v_mfma_f32_16x16x32_bf16 v[50:53], v[146:149], v[162:165], v[50:53]
	v_mfma_f32_16x16x32_bf16 v[38:41], v[130:133], v[170:173], v[38:41]
	v_mfma_f32_16x16x32_bf16 v[34:37], v[146:149], v[170:173], v[34:37]
	v_mfma_f32_16x16x32_bf16 v[22:25], v[130:133], v[196:199], v[22:25]
	v_mfma_f32_16x16x32_bf16 v[18:21], v[146:149], v[196:199], v[18:21]
	v_mfma_f32_16x16x32_bf16 v[6:9], v[130:133], v[204:207], v[6:9]
	v_mfma_f32_16x16x32_bf16 v[2:5], v[146:149], v[204:207], v[2:5]
	v_mfma_f32_16x16x32_bf16 v[54:57], v[142:145], v[166:169], v[54:57]
	v_mfma_f32_16x16x32_bf16 v[50:53], v[158:161], v[166:169], v[50:53]
	v_mfma_f32_16x16x32_bf16 v[38:41], v[142:145], v[192:195], v[38:41]
	v_mfma_f32_16x16x32_bf16 v[34:37], v[158:161], v[192:195], v[34:37]
	v_mfma_f32_16x16x32_bf16 v[22:25], v[142:145], v[200:203], v[22:25]
	v_mfma_f32_16x16x32_bf16 v[18:21], v[158:161], v[200:203], v[18:21]
	v_mfma_f32_16x16x32_bf16 v[6:9], v[142:145], v[208:211], v[6:9]
	v_mfma_f32_16x16x32_bf16 v[2:5], v[158:161], v[208:211], v[2:5]
	s_setprio 0
	s_barrier
	s_add_i32 s60, s60, 2
	s_add_u32 s19, s19, 0x100
	s_addc_u32 s21, s21, 0
	s_cmpk_gt_u32 s60, 0x55
	s_mov_b64 s[26:27], s[8:9]
